# grid barrier: non-leader workgroups poll the cross-XCD generation word directly instead of waiting for the per-XCD relay
# baseline (speedup 1.0000x reference)
; __device__ __forceinline__ unsigned xb_ld(unsigned* p)              { return __hip_atomic_load(p, __ATOMIC_RELAXED, __HIP_MEMORY_SCOPE_AGENT); }
; __device__ __forceinline__ unsigned xb_add(unsigned* p, unsigned v) { return __hip_atomic_fetch_add(p, v, __ATOMIC_RELAXED, __HIP_MEMORY_SCOPE_AGENT); }
; #define XB_SPIN(cond, bar) do { unsigned _sp = 0; while (cond) { __builtin_amdgcn_s_sleep(1); \
;     if ((++_sp & 255u) == 0u) { if (xb_ld(&(bar)[XB_TMO])) break; if (_sp > XB_SPIN_CAP) { atomicAdd(&(bar)[XB_TMO], 1u); break; } } } } while (0)
; __device__ __forceinline__ void xcd_barrier(const XcdBarrier& b) {
;     ...
;         const unsigned old = xb_add(&bar[XB_XSUB(b.x)], 1u);
;         const unsigned gen = old / nloc;
;         if (old + 1u == (gen + 1u) * nloc) {
;             __builtin_amdgcn_fence(__ATOMIC_RELEASE, "agent");
;             asm volatile("s_waitcnt vmcnt(0)" ::: "memory");
;             const unsigned og = xb_add(&bar[XB_TOP], 1u);
;             const unsigned tg = og / nx;
;             if (og + 1u == (tg + 1u) * nx) xb_add(&bar[XB_TOPGEN], 1u);
;             else XB_SPIN(xb_ld(&bar[XB_TOPGEN]) == tg, bar);
;             __builtin_amdgcn_fence(__ATOMIC_ACQUIRE, "agent");
;             xb_add(&bar[XB_XGEN(b.x)], 1u);
;             asm volatile("s_waitcnt vmcnt(0)" ::: "memory");
;         } else {
;             XB_SPIN(xb_ld(&bar[XB_XGEN(b.x)]) == gen, bar);
;             __builtin_amdgcn_fence(__ATOMIC_ACQUIRE, "agent");
;             asm volatile("s_waitcnt vmcnt(0)" ::: "memory");
;         }
.LBB0_317:
	s_or_b64 exec, exec, s[12:13]
	v_cvt_f32_u32_e32 v5, v3
	s_waitcnt vmcnt(0)
	v_readfirstlane_b32 s0, v4
	v_sub_u32_e32 v4, 0, v3
	v_rcp_iflag_f32_e32 v5, v5
	v_add_u32_e32 v6, s0, v2
	v_mul_f32_e32 v5, 0x4f7ffffe, v5
	v_cvt_u32_f32_e32 v5, v5
	v_mul_lo_u32 v2, v4, v5
	v_mul_hi_u32 v2, v5, v2
	v_add_u32_e32 v2, v5, v2
	v_mul_hi_u32 v2, v6, v2
	v_mul_lo_u32 v4, v2, v3
	v_sub_u32_e32 v4, v6, v4
	v_add_u32_e32 v5, 1, v2
	v_cmp_ge_u32_e32 vcc, v4, v3
	s_nop 1
	v_cndmask_b32_e32 v2, v2, v5, vcc
	v_sub_u32_e32 v5, v4, v3
	v_cndmask_b32_e32 v4, v4, v5, vcc
	v_add_u32_e32 v5, 1, v2
	v_cmp_ge_u32_e32 vcc, v4, v3
	v_add_u32_e32 v4, 1, v6
	s_nop 0
	v_cndmask_b32_e32 v2, v2, v5, vcc
	v_mul_lo_u32 v5, v3, v2
	v_add_u32_e32 v3, v5, v3
	v_cmp_ne_u32_e32 vcc, v4, v3
	s_and_saveexec_b64 s[0:1], vcc
	s_xor_b64 s[10:11], exec, s[0:1]
	s_cbranch_execz .LBB0_331
	s_waitcnt lgkmcnt(0)
	v_readlane_b32 s16, v255, 0
	v_readlane_b32 s17, v255, 1
	s_add_u32 s16, s16, 0x7500
	s_addc_u32 s17, s17, 0
	v_mov_b32_e32 v1, 0
	global_load_dword v1, v1, s[16:17] sc1
	s_waitcnt vmcnt(0)
	v_cmp_eq_u32_e32 vcc, v1, v2
	s_and_saveexec_b64 s[12:13], vcc
	s_cbranch_execz .LBB0_330
	v_readlane_b32 s0, v255, 0
	v_readlane_b32 s1, v255, 1
	s_add_u32 s14, s0, 0x4200
	s_addc_u32 s15, s1, 0
	s_mov_b32 s0, 1
	s_mov_b64 s[18:19], 0
	v_mov_b32_e32 v1, 0
	s_branch .LBB0_321

; __device__ __forceinline__ unsigned xb_ld(unsigned* p)              { return __hip_atomic_load(p, __ATOMIC_RELAXED, __HIP_MEMORY_SCOPE_AGENT); }
; __device__ __forceinline__ unsigned xb_add(unsigned* p, unsigned v) { return __hip_atomic_fetch_add(p, v, __ATOMIC_RELAXED, __HIP_MEMORY_SCOPE_AGENT); }
; #define XB_SPIN(cond, bar) do { unsigned _sp = 0; while (cond) { __builtin_amdgcn_s_sleep(1); \
;     if ((++_sp & 255u) == 0u) { if (xb_ld(&(bar)[XB_TMO])) break; if (_sp > XB_SPIN_CAP) { atomicAdd(&(bar)[XB_TMO], 1u); break; } } } } while (0)
; __device__ __forceinline__ void xcd_barrier(const XcdBarrier& b) {
;     ...
;         const unsigned old = xb_add(&bar[XB_XSUB(b.x)], 1u);
;         const unsigned gen = old / nloc;
;         if (old + 1u == (gen + 1u) * nloc) {
;             __builtin_amdgcn_fence(__ATOMIC_RELEASE, "agent");
;             asm volatile("s_waitcnt vmcnt(0)" ::: "memory");
;             const unsigned og = xb_add(&bar[XB_TOP], 1u);
;             const unsigned tg = og / nx;
;             if (og + 1u == (tg + 1u) * nx) xb_add(&bar[XB_TOPGEN], 1u);
;             else XB_SPIN(xb_ld(&bar[XB_TOPGEN]) == tg, bar);
;             __builtin_amdgcn_fence(__ATOMIC_ACQUIRE, "agent");
;             xb_add(&bar[XB_XGEN(b.x)], 1u);
;             asm volatile("s_waitcnt vmcnt(0)" ::: "memory");
;         } else {
;             XB_SPIN(xb_ld(&bar[XB_XGEN(b.x)]) == gen, bar);
;             __builtin_amdgcn_fence(__ATOMIC_ACQUIRE, "agent");
;             asm volatile("s_waitcnt vmcnt(0)" ::: "memory");
;         }
.LBB0_1235:
	s_or_b64 exec, exec, s[12:13]
	v_cvt_f32_u32_e32 v1, v4
	s_waitcnt vmcnt(0)
	v_readfirstlane_b32 s0, v5
	v_sub_u32_e32 v5, 0, v4
	v_rcp_iflag_f32_e32 v1, v1
	v_add_u32_e32 v6, s0, v3
	v_mul_f32_e32 v1, 0x4f7ffffe, v1
	v_cvt_u32_f32_e32 v1, v1
	v_mul_lo_u32 v3, v5, v1
	v_mul_hi_u32 v3, v1, v3
	v_add_u32_e32 v1, v1, v3
	v_mul_hi_u32 v1, v6, v1
	v_mul_lo_u32 v3, v1, v4
	v_sub_u32_e32 v3, v6, v3
	v_add_u32_e32 v5, 1, v1
	v_cmp_ge_u32_e32 vcc, v3, v4
	s_nop 1
	v_cndmask_b32_e32 v1, v1, v5, vcc
	v_sub_u32_e32 v5, v3, v4
	v_cndmask_b32_e32 v3, v3, v5, vcc
	v_add_u32_e32 v5, 1, v1
	v_cmp_ge_u32_e32 vcc, v3, v4
	s_nop 1
	v_cndmask_b32_e32 v3, v1, v5, vcc
	v_mul_lo_u32 v5, v4, v3
	v_add_u32_e32 v1, 1, v6
	v_add_u32_e32 v4, v5, v4
	v_cmp_ne_u32_e32 vcc, v1, v4
	s_and_saveexec_b64 s[0:1], vcc
	s_xor_b64 s[10:11], exec, s[0:1]
	s_cbranch_execz .LBB0_1249
	v_readlane_b32 s16, v255, 0
	v_readlane_b32 s17, v255, 1
	s_add_u32 s16, s16, 0x7500
	s_addc_u32 s17, s17, 0
	v_mov_b32_e32 v1, 0
	global_load_dword v1, v1, s[16:17] sc1
	s_waitcnt vmcnt(0)
	v_cmp_eq_u32_e32 vcc, v1, v3
	s_and_saveexec_b64 s[12:13], vcc
	s_cbranch_execz .LBB0_1248
	v_readlane_b32 s0, v255, 0
	v_readlane_b32 s1, v255, 1
	s_add_u32 s14, s0, 0x4200
	s_addc_u32 s15, s1, 0
	s_mov_b32 s0, 1
	s_mov_b64 s[18:19], 0
	s_waitcnt lgkmcnt(0)
	v_mov_b32_e32 v2, 0
	s_branch .LBB0_1239

; __device__ __forceinline__ unsigned xb_ld(unsigned* p)              { return __hip_atomic_load(p, __ATOMIC_RELAXED, __HIP_MEMORY_SCOPE_AGENT); }
; __device__ __forceinline__ unsigned xb_add(unsigned* p, unsigned v) { return __hip_atomic_fetch_add(p, v, __ATOMIC_RELAXED, __HIP_MEMORY_SCOPE_AGENT); }
; #define XB_SPIN(cond, bar) do { unsigned _sp = 0; while (cond) { __builtin_amdgcn_s_sleep(1); \
;     if ((++_sp & 255u) == 0u) { if (xb_ld(&(bar)[XB_TMO])) break; if (_sp > XB_SPIN_CAP) { atomicAdd(&(bar)[XB_TMO], 1u); break; } } } } while (0)
; __device__ __forceinline__ void xcd_barrier(const XcdBarrier& b) {
;     ...
;         const unsigned old = xb_add(&bar[XB_XSUB(b.x)], 1u);
;         const unsigned gen = old / nloc;
;         if (old + 1u == (gen + 1u) * nloc) {
;             __builtin_amdgcn_fence(__ATOMIC_RELEASE, "agent");
;             asm volatile("s_waitcnt vmcnt(0)" ::: "memory");
;             const unsigned og = xb_add(&bar[XB_TOP], 1u);
;             const unsigned tg = og / nx;
;             if (og + 1u == (tg + 1u) * nx) xb_add(&bar[XB_TOPGEN], 1u);
;             else XB_SPIN(xb_ld(&bar[XB_TOPGEN]) == tg, bar);
;             __builtin_amdgcn_fence(__ATOMIC_ACQUIRE, "agent");
;             xb_add(&bar[XB_XGEN(b.x)], 1u);
;             asm volatile("s_waitcnt vmcnt(0)" ::: "memory");
;         } else {
;             XB_SPIN(xb_ld(&bar[XB_XGEN(b.x)]) == gen, bar);
;             __builtin_amdgcn_fence(__ATOMIC_ACQUIRE, "agent");
;             asm volatile("s_waitcnt vmcnt(0)" ::: "memory");
;         }
.LBB0_2429:
	s_or_b64 exec, exec, s[12:13]
	v_cvt_f32_u32_e32 v1, v4
	s_waitcnt vmcnt(0)
	v_readfirstlane_b32 s1, v5
	v_sub_u32_e32 v5, 0, v4
	v_rcp_iflag_f32_e32 v1, v1
	v_add_u32_e32 v6, s1, v3
	v_mul_f32_e32 v1, 0x4f7ffffe, v1
	v_cvt_u32_f32_e32 v1, v1
	v_mul_lo_u32 v3, v5, v1
	v_mul_hi_u32 v3, v1, v3
	v_add_u32_e32 v1, v1, v3
	v_mul_hi_u32 v1, v6, v1
	v_mul_lo_u32 v3, v1, v4
	v_sub_u32_e32 v3, v6, v3
	v_add_u32_e32 v5, 1, v1
	v_cmp_ge_u32_e32 vcc, v3, v4
	s_nop 1
	v_cndmask_b32_e32 v1, v1, v5, vcc
	v_sub_u32_e32 v5, v3, v4
	v_cndmask_b32_e32 v3, v3, v5, vcc
	v_add_u32_e32 v5, 1, v1
	v_cmp_ge_u32_e32 vcc, v3, v4
	s_nop 1
	v_cndmask_b32_e32 v3, v1, v5, vcc
	v_mul_lo_u32 v5, v4, v3
	v_add_u32_e32 v1, 1, v6
	v_add_u32_e32 v4, v5, v4
	v_cmp_ne_u32_e32 vcc, v1, v4
	s_and_saveexec_b64 s[4:5], vcc
	s_xor_b64 s[10:11], exec, s[4:5]
	s_cbranch_execz .LBB0_2443
	v_readlane_b32 s16, v255, 0
	v_readlane_b32 s17, v255, 1
	s_add_u32 s16, s16, 0x7500
	s_addc_u32 s17, s17, 0
	v_mov_b32_e32 v1, 0
	global_load_dword v1, v1, s[16:17] sc1
	s_waitcnt vmcnt(0)
	v_cmp_eq_u32_e32 vcc, v1, v3
	s_and_saveexec_b64 s[12:13], vcc
	s_cbranch_execz .LBB0_2442
	v_readlane_b32 s4, v255, 0
	v_readlane_b32 s5, v255, 1
	s_add_u32 s14, s4, 0x4200
	s_addc_u32 s15, s5, 0
	s_mov_b32 s1, 1
	s_mov_b64 s[18:19], 0
	s_waitcnt lgkmcnt(0)
	v_mov_b32_e32 v2, 0
	s_branch .LBB0_2433

; __device__ __forceinline__ unsigned xb_ld(unsigned* p)              { return __hip_atomic_load(p, __ATOMIC_RELAXED, __HIP_MEMORY_SCOPE_AGENT); }
; __device__ __forceinline__ unsigned xb_add(unsigned* p, unsigned v) { return __hip_atomic_fetch_add(p, v, __ATOMIC_RELAXED, __HIP_MEMORY_SCOPE_AGENT); }
; #define XB_SPIN(cond, bar) do { unsigned _sp = 0; while (cond) { __builtin_amdgcn_s_sleep(1); \
;     if ((++_sp & 255u) == 0u) { if (xb_ld(&(bar)[XB_TMO])) break; if (_sp > XB_SPIN_CAP) { atomicAdd(&(bar)[XB_TMO], 1u); break; } } } } while (0)
; __device__ __forceinline__ void xcd_barrier(const XcdBarrier& b) {
;     ...
;         const unsigned old = xb_add(&bar[XB_XSUB(b.x)], 1u);
;         const unsigned gen = old / nloc;
;         if (old + 1u == (gen + 1u) * nloc) {
;             __builtin_amdgcn_fence(__ATOMIC_RELEASE, "agent");
;             asm volatile("s_waitcnt vmcnt(0)" ::: "memory");
;             const unsigned og = xb_add(&bar[XB_TOP], 1u);
;             const unsigned tg = og / nx;
;             if (og + 1u == (tg + 1u) * nx) xb_add(&bar[XB_TOPGEN], 1u);
;             else XB_SPIN(xb_ld(&bar[XB_TOPGEN]) == tg, bar);
;             __builtin_amdgcn_fence(__ATOMIC_ACQUIRE, "agent");
;             xb_add(&bar[XB_XGEN(b.x)], 1u);
;             asm volatile("s_waitcnt vmcnt(0)" ::: "memory");
;         } else {
;             XB_SPIN(xb_ld(&bar[XB_XGEN(b.x)]) == gen, bar);
;             __builtin_amdgcn_fence(__ATOMIC_ACQUIRE, "agent");
;             asm volatile("s_waitcnt vmcnt(0)" ::: "memory");
;         }
.LBB0_2536:
	s_or_b64 exec, exec, s[12:13]
	v_cvt_f32_u32_e32 v5, v3
	s_waitcnt vmcnt(0)
	v_readfirstlane_b32 s1, v4
	v_sub_u32_e32 v4, 0, v3
	v_rcp_iflag_f32_e32 v5, v5
	v_add_u32_e32 v6, s1, v2
	v_mul_f32_e32 v5, 0x4f7ffffe, v5
	v_cvt_u32_f32_e32 v5, v5
	v_mul_lo_u32 v2, v4, v5
	v_mul_hi_u32 v2, v5, v2
	v_add_u32_e32 v2, v5, v2
	v_mul_hi_u32 v2, v6, v2
	v_mul_lo_u32 v4, v2, v3
	v_sub_u32_e32 v4, v6, v4
	v_add_u32_e32 v5, 1, v2
	v_cmp_ge_u32_e32 vcc, v4, v3
	s_nop 1
	v_cndmask_b32_e32 v2, v2, v5, vcc
	v_sub_u32_e32 v5, v4, v3
	v_cndmask_b32_e32 v4, v4, v5, vcc
	v_add_u32_e32 v5, 1, v2
	v_cmp_ge_u32_e32 vcc, v4, v3
	v_add_u32_e32 v4, 1, v6
	s_nop 0
	v_cndmask_b32_e32 v2, v2, v5, vcc
	v_mul_lo_u32 v5, v3, v2
	v_add_u32_e32 v3, v5, v3
	v_cmp_ne_u32_e32 vcc, v4, v3
	s_and_saveexec_b64 s[10:11], vcc
	s_xor_b64 s[10:11], exec, s[10:11]
	s_cbranch_execz .LBB0_2550
	s_waitcnt lgkmcnt(0)
	v_readlane_b32 s16, v255, 0
	v_readlane_b32 s17, v255, 1
	s_add_u32 s16, s16, 0x7500
	s_addc_u32 s17, s17, 0
	v_mov_b32_e32 v1, 0
	global_load_dword v1, v1, s[16:17] sc1
	s_waitcnt vmcnt(0)
	v_cmp_eq_u32_e32 vcc, v1, v2
	s_and_saveexec_b64 s[12:13], vcc
	s_cbranch_execz .LBB0_2549
	v_readlane_b32 s14, v255, 0
	v_readlane_b32 s15, v255, 1
	s_add_u32 s14, s14, 0x4200
	s_addc_u32 s15, s15, 0
	s_mov_b32 s1, 1
	s_mov_b64 s[18:19], 0
	v_mov_b32_e32 v1, 0
	s_branch .LBB0_2540

; __device__ __forceinline__ unsigned xb_ld(unsigned* p)              { return __hip_atomic_load(p, __ATOMIC_RELAXED, __HIP_MEMORY_SCOPE_AGENT); }
; __device__ __forceinline__ unsigned xb_add(unsigned* p, unsigned v) { return __hip_atomic_fetch_add(p, v, __ATOMIC_RELAXED, __HIP_MEMORY_SCOPE_AGENT); }
; #define XB_SPIN(cond, bar) do { unsigned _sp = 0; while (cond) { __builtin_amdgcn_s_sleep(1); \
;     if ((++_sp & 255u) == 0u) { if (xb_ld(&(bar)[XB_TMO])) break; if (_sp > XB_SPIN_CAP) { atomicAdd(&(bar)[XB_TMO], 1u); break; } } } } while (0)
; __device__ __forceinline__ void xcd_barrier(const XcdBarrier& b) {
;     ...
;         const unsigned old = xb_add(&bar[XB_XSUB(b.x)], 1u);
;         const unsigned gen = old / nloc;
;         if (old + 1u == (gen + 1u) * nloc) {
;             __builtin_amdgcn_fence(__ATOMIC_RELEASE, "agent");
;             asm volatile("s_waitcnt vmcnt(0)" ::: "memory");
;             const unsigned og = xb_add(&bar[XB_TOP], 1u);
;             const unsigned tg = og / nx;
;             if (og + 1u == (tg + 1u) * nx) xb_add(&bar[XB_TOPGEN], 1u);
;             else XB_SPIN(xb_ld(&bar[XB_TOPGEN]) == tg, bar);
;             __builtin_amdgcn_fence(__ATOMIC_ACQUIRE, "agent");
;             xb_add(&bar[XB_XGEN(b.x)], 1u);
;             asm volatile("s_waitcnt vmcnt(0)" ::: "memory");
;         } else {
;             XB_SPIN(xb_ld(&bar[XB_XGEN(b.x)]) == gen, bar);
;             __builtin_amdgcn_fence(__ATOMIC_ACQUIRE, "agent");
;             asm volatile("s_waitcnt vmcnt(0)" ::: "memory");
;         }
.LBB0_3570:
	s_or_b64 exec, exec, s[8:9]
	v_cvt_f32_u32_e32 v5, v3
	s_waitcnt vmcnt(0)
	v_readfirstlane_b32 s0, v4
	v_sub_u32_e32 v4, 0, v3
	v_rcp_iflag_f32_e32 v5, v5
	v_add_u32_e32 v6, s0, v2
	v_mul_f32_e32 v5, 0x4f7ffffe, v5
	v_cvt_u32_f32_e32 v5, v5
	v_mul_lo_u32 v2, v4, v5
	v_mul_hi_u32 v2, v5, v2
	v_add_u32_e32 v2, v5, v2
	v_mul_hi_u32 v2, v6, v2
	v_mul_lo_u32 v4, v2, v3
	v_sub_u32_e32 v4, v6, v4
	v_add_u32_e32 v5, 1, v2
	v_cmp_ge_u32_e32 vcc, v4, v3
	s_nop 1
	v_cndmask_b32_e32 v2, v2, v5, vcc
	v_sub_u32_e32 v5, v4, v3
	v_cndmask_b32_e32 v4, v4, v5, vcc
	v_add_u32_e32 v5, 1, v2
	v_cmp_ge_u32_e32 vcc, v4, v3
	v_add_u32_e32 v4, 1, v6
	s_nop 0
	v_cndmask_b32_e32 v2, v2, v5, vcc
	v_mul_lo_u32 v5, v3, v2
	v_add_u32_e32 v3, v5, v3
	v_cmp_ne_u32_e32 vcc, v4, v3
	s_and_saveexec_b64 s[0:1], vcc
	s_xor_b64 s[6:7], exec, s[0:1]
	s_cbranch_execz .LBB0_3584
	s_waitcnt lgkmcnt(0)
	v_readlane_b32 s12, v255, 0
	v_readlane_b32 s13, v255, 1
	s_add_u32 s12, s12, 0x7500
	s_addc_u32 s13, s13, 0
	v_mov_b32_e32 v1, 0
	global_load_dword v1, v1, s[12:13] sc1
	s_waitcnt vmcnt(0)
	v_cmp_eq_u32_e32 vcc, v1, v2
	s_and_saveexec_b64 s[8:9], vcc
	s_cbranch_execz .LBB0_3583
	v_readlane_b32 s0, v255, 0
	v_readlane_b32 s1, v255, 1
	s_add_u32 s10, s0, 0x4200
	s_addc_u32 s11, s1, 0
	s_mov_b32 s0, 1
	s_mov_b64 s[14:15], 0
	v_mov_b32_e32 v1, 0
	s_branch .LBB0_3574
